# DeltaNet prep forward substitution in 4-row blocks (independent partial sums, operand rows loaded one block ahead, in-block triangular fix-up); f32 VALU as before
# baseline (speedup 1.0000x reference)
.LBB0_523:
	v_and_b32_e32 v2, 7, v80
	v_lshrrev_b32_e32 v0, 3, v81
	v_or_b32_e32 v0, v10, v0
	v_lshlrev_b32_e32 v128, 5, v2
	v_add_u32_e32 v128, 0xd400, v128
	v_mov_b32_e32 v129, 0xd400
	ds_read_b128 v[206:209], v128 offset:256
	ds_read_b128 v[214:217], v128 offset:512
	ds_read_b128 v[222:225], v128 offset:768
	ds_read_b32 v130, v129 offset:544
	ds_read_b32 v131, v129 offset:800
	ds_read_b32 v132, v129 offset:832
	v_cmp_eq_u32_e64 s[6:7], 0, v2
	v_cmp_eq_u32_e64 s[8:9], 1, v2
	v_cmp_eq_u32_e64 s[10:11], 2, v2
	v_cmp_eq_u32_e64 s[12:13], 3, v2
	v_cmp_eq_u32_e64 s[14:15], 4, v2
	v_cmp_eq_u32_e64 s[16:17], 5, v2
	v_cmp_eq_u32_e64 s[18:19], 6, v2
	v_cmp_eq_u32_e64 s[20:21], 7, v2
	v_mov_b32_e32 v101, 0
	v_mov_b32_e32 v102, 0
	v_mov_b32_e32 v103, 0
	v_mov_b32_e32 v104, 0
	v_mov_b32_e32 v105, 0
	v_mov_b32_e32 v106, 0
	v_mov_b32_e32 v107, 0
	v_or_b32_e32 v152, v2, v0
	v_cmp_eq_u32_e32 vcc, 0, v152
	s_nop 1
	v_cndmask_b32_e64 v100, 0, 1.0, vcc
	v_cmp_eq_u32_e32 vcc, 1, v0
	s_nop 1
	v_cndmask_b32_e64 v116, 0, 1.0, vcc
	v_cmp_eq_u32_e32 vcc, 2, v0
	s_nop 1
	v_cndmask_b32_e64 v117, 0, 1.0, vcc
	v_cmp_eq_u32_e32 vcc, 3, v0
	s_nop 1
	v_cndmask_b32_e64 v118, 0, 1.0, vcc
	s_waitcnt lgkmcnt(5)
	v_mul_f32_e32 v108, v206, v100
	s_waitcnt lgkmcnt(4)
	v_mul_f32_e32 v109, v214, v100
	s_waitcnt lgkmcnt(3)
	v_mul_f32_e32 v110, v222, v100
	s_waitcnt lgkmcnt(0)
	ds_read_b128 v[176:179], v128 offset:1024
	ds_read_b128 v[184:187], v128 offset:1280
	ds_read_b128 v[192:195], v128 offset:1536
	ds_read_b128 v[200:203], v128 offset:1792
	ds_read_b32 v146, v129 offset:1408
	ds_read_b32 v147, v129 offset:1664
	ds_read_b32 v148, v129 offset:1696
	ds_read_b32 v149, v129 offset:1920
	ds_read_b32 v150, v129 offset:1952
	ds_read_b32 v151, v129 offset:1984
	v_add_f32_dpp v108, v108, v108 quad_perm:[1,0,3,2] row_mask:0xf bank_mask:0xf bound_ctrl:1
	v_add_f32_dpp v109, v109, v109 quad_perm:[1,0,3,2] row_mask:0xf bank_mask:0xf bound_ctrl:1
	v_cmp_eq_u32_e32 vcc, 4, v0
	v_add_f32_dpp v110, v110, v110 quad_perm:[1,0,3,2] row_mask:0xf bank_mask:0xf bound_ctrl:1
	s_nop 0
	v_cndmask_b32_e64 v120, 0, 1.0, vcc
	v_cmp_eq_u32_e32 vcc, 5, v0
	v_add_f32_dpp v108, v108, v108 quad_perm:[2,3,0,1] row_mask:0xf bank_mask:0xf bound_ctrl:1
	v_add_f32_dpp v109, v109, v109 quad_perm:[2,3,0,1] row_mask:0xf bank_mask:0xf bound_ctrl:1
	v_cndmask_b32_e64 v121, 0, 1.0, vcc
	v_cmp_eq_u32_e32 vcc, 6, v0
	v_add_f32_dpp v110, v110, v110 quad_perm:[2,3,0,1] row_mask:0xf bank_mask:0xf bound_ctrl:1
	s_nop 0
	v_cndmask_b32_e64 v122, 0, 1.0, vcc
	v_cmp_eq_u32_e32 vcc, 7, v0
	v_add_f32_dpp v108, v108, v108 row_half_mirror row_mask:0xf bank_mask:0xf bound_ctrl:1
	v_add_f32_dpp v109, v109, v109 row_half_mirror row_mask:0xf bank_mask:0xf bound_ctrl:1
	v_cndmask_b32_e64 v123, 0, 1.0, vcc
	v_add_f32_dpp v110, v110, v110 row_half_mirror row_mask:0xf bank_mask:0xf bound_ctrl:1
	v_sub_f32_e32 v124, v116, v108
	v_sub_f32_e32 v125, v117, v109
	v_sub_f32_e32 v126, v118, v110
	v_fma_f32 v125, -v130, v124, v125
	v_fma_f32 v126, -v131, v124, v126
	v_fma_f32 v126, -v132, v125, v126
	v_cndmask_b32_e64 v100, v100, v124, s[8:9]
	v_cndmask_b32_e64 v100, v100, v125, s[10:11]
	v_cndmask_b32_e64 v100, v100, v126, s[12:13]
	s_waitcnt lgkmcnt(9)
	v_mul_f32_e32 v112, v176, v100
	s_waitcnt lgkmcnt(8)
	v_mul_f32_e32 v113, v184, v100
	s_waitcnt lgkmcnt(7)
	v_mul_f32_e32 v114, v192, v100
	s_waitcnt lgkmcnt(6)
	v_mul_f32_e32 v115, v200, v100
	s_waitcnt lgkmcnt(0)
	ds_read_b128 v[206:209], v128 offset:2048
	ds_read_b128 v[214:217], v128 offset:2304
	ds_read_b128 v[222:225], v128 offset:2560
	ds_read_b128 v[230:233], v128 offset:2816
	ds_read_b32 v130, v129 offset:2308
	ds_read_b32 v131, v129 offset:2564
	ds_read_b32 v132, v129 offset:2596
	ds_read_b32 v133, v129 offset:2820
	ds_read_b32 v134, v129 offset:2852
	ds_read_b32 v135, v129 offset:2884
	v_add_f32_dpp v112, v112, v112 quad_perm:[1,0,3,2] row_mask:0xf bank_mask:0xf bound_ctrl:1
	v_add_f32_dpp v113, v113, v113 quad_perm:[1,0,3,2] row_mask:0xf bank_mask:0xf bound_ctrl:1
	v_cmp_eq_u32_e32 vcc, 8, v0
	v_add_f32_dpp v114, v114, v114 quad_perm:[1,0,3,2] row_mask:0xf bank_mask:0xf bound_ctrl:1
	v_add_f32_dpp v115, v115, v115 quad_perm:[1,0,3,2] row_mask:0xf bank_mask:0xf bound_ctrl:1
	v_cndmask_b32_e64 v116, 0, 1.0, vcc
	v_cmp_eq_u32_e32 vcc, 9, v0
	v_add_f32_dpp v112, v112, v112 quad_perm:[2,3,0,1] row_mask:0xf bank_mask:0xf bound_ctrl:1
	v_add_f32_dpp v113, v113, v113 quad_perm:[2,3,0,1] row_mask:0xf bank_mask:0xf bound_ctrl:1
	v_cndmask_b32_e64 v117, 0, 1.0, vcc
	v_cmp_eq_u32_e32 vcc, 10, v0
	v_add_f32_dpp v114, v114, v114 quad_perm:[2,3,0,1] row_mask:0xf bank_mask:0xf bound_ctrl:1
	v_add_f32_dpp v115, v115, v115 quad_perm:[2,3,0,1] row_mask:0xf bank_mask:0xf bound_ctrl:1
	v_cndmask_b32_e64 v118, 0, 1.0, vcc
	v_cmp_eq_u32_e32 vcc, 11, v0
	v_add_f32_dpp v112, v112, v112 row_half_mirror row_mask:0xf bank_mask:0xf bound_ctrl:1
	v_add_f32_dpp v113, v113, v113 row_half_mirror row_mask:0xf bank_mask:0xf bound_ctrl:1
	v_cndmask_b32_e64 v119, 0, 1.0, vcc
	v_add_f32_dpp v114, v114, v114 row_half_mirror row_mask:0xf bank_mask:0xf bound_ctrl:1
	v_add_f32_dpp v115, v115, v115 row_half_mirror row_mask:0xf bank_mask:0xf bound_ctrl:1
	v_sub_f32_e32 v124, v120, v112
	v_sub_f32_e32 v125, v121, v113
	v_sub_f32_e32 v126, v122, v114
	v_sub_f32_e32 v127, v123, v115
	v_fma_f32 v125, -v146, v124, v125
	v_fma_f32 v126, -v147, v124, v126
	v_fma_f32 v127, -v149, v124, v127
	v_fma_f32 v126, -v148, v125, v126
	v_fma_f32 v127, -v150, v125, v127
	v_fma_f32 v127, -v151, v126, v127
	v_cndmask_b32_e64 v100, v100, v124, s[14:15]
	v_cndmask_b32_e64 v100, v100, v125, s[16:17]
	v_cndmask_b32_e64 v100, v100, v126, s[18:19]
	v_cndmask_b32_e64 v100, v100, v127, s[20:21]
	s_waitcnt lgkmcnt(9)
	v_mul_f32_e32 v108, v206, v100
	s_waitcnt lgkmcnt(8)
	v_mul_f32_e32 v109, v214, v100
	s_waitcnt lgkmcnt(7)
	v_mul_f32_e32 v110, v222, v100
	s_waitcnt lgkmcnt(6)
	v_mul_f32_e32 v111, v230, v100
	s_waitcnt lgkmcnt(0)
	ds_read_b128 v[176:179], v128 offset:3072
	ds_read_b128 v[184:187], v128 offset:3328
	ds_read_b128 v[192:195], v128 offset:3584
	ds_read_b128 v[200:203], v128 offset:3840
	ds_read_b32 v146, v129 offset:3460
	ds_read_b32 v147, v129 offset:3716
	ds_read_b32 v148, v129 offset:3748
	ds_read_b32 v149, v129 offset:3972
	ds_read_b32 v150, v129 offset:4004
	ds_read_b32 v151, v129 offset:4036
	v_add_f32_dpp v108, v108, v108 quad_perm:[1,0,3,2] row_mask:0xf bank_mask:0xf bound_ctrl:1
	v_add_f32_dpp v109, v109, v109 quad_perm:[1,0,3,2] row_mask:0xf bank_mask:0xf bound_ctrl:1
	v_cmp_eq_u32_e32 vcc, 12, v0
	v_add_f32_dpp v110, v110, v110 quad_perm:[1,0,3,2] row_mask:0xf bank_mask:0xf bound_ctrl:1
	v_add_f32_dpp v111, v111, v111 quad_perm:[1,0,3,2] row_mask:0xf bank_mask:0xf bound_ctrl:1
	v_cndmask_b32_e64 v120, 0, 1.0, vcc
	v_cmp_eq_u32_e32 vcc, 13, v0
	v_add_f32_dpp v108, v108, v108 quad_perm:[2,3,0,1] row_mask:0xf bank_mask:0xf bound_ctrl:1
	v_add_f32_dpp v109, v109, v109 quad_perm:[2,3,0,1] row_mask:0xf bank_mask:0xf bound_ctrl:1
	v_cndmask_b32_e64 v121, 0, 1.0, vcc
	v_cmp_eq_u32_e32 vcc, 14, v0
	v_add_f32_dpp v110, v110, v110 quad_perm:[2,3,0,1] row_mask:0xf bank_mask:0xf bound_ctrl:1
	v_add_f32_dpp v111, v111, v111 quad_perm:[2,3,0,1] row_mask:0xf bank_mask:0xf bound_ctrl:1
	v_cndmask_b32_e64 v122, 0, 1.0, vcc
	v_cmp_eq_u32_e32 vcc, 15, v0
	v_add_f32_dpp v108, v108, v108 row_half_mirror row_mask:0xf bank_mask:0xf bound_ctrl:1
	v_add_f32_dpp v109, v109, v109 row_half_mirror row_mask:0xf bank_mask:0xf bound_ctrl:1
	v_cndmask_b32_e64 v123, 0, 1.0, vcc
	v_add_f32_dpp v110, v110, v110 row_half_mirror row_mask:0xf bank_mask:0xf bound_ctrl:1
	v_add_f32_dpp v111, v111, v111 row_half_mirror row_mask:0xf bank_mask:0xf bound_ctrl:1
	v_sub_f32_e32 v124, v116, v108
	v_sub_f32_e32 v125, v117, v109
	v_sub_f32_e32 v126, v118, v110
	v_sub_f32_e32 v127, v119, v111
	v_fma_f32 v125, -v130, v124, v125
	v_fma_f32 v126, -v131, v124, v126
	v_fma_f32 v127, -v133, v124, v127
	s_waitcnt lgkmcnt(9)
	v_mul_f32_e32 v112, v176, v100
	s_waitcnt lgkmcnt(8)
	v_mul_f32_e32 v113, v184, v100
	v_fma_f32 v126, -v132, v125, v126
	v_fma_f32 v127, -v134, v125, v127
	s_waitcnt lgkmcnt(7)
	v_mul_f32_e32 v114, v192, v100
	s_waitcnt lgkmcnt(6)
	v_mul_f32_e32 v115, v200, v100
	v_fma_f32 v127, -v135, v126, v127
	v_cndmask_b32_e64 v101, v101, v124, s[6:7]
	v_cndmask_b32_e64 v101, v101, v125, s[8:9]
	v_cndmask_b32_e64 v101, v101, v126, s[10:11]
	v_cndmask_b32_e64 v101, v101, v127, s[12:13]
	v_fmac_f32_e32 v112, v177, v101
	v_fmac_f32_e32 v113, v185, v101
	v_fmac_f32_e32 v114, v193, v101
	v_fmac_f32_e32 v115, v201, v101
	s_waitcnt lgkmcnt(0)
	ds_read_b128 v[206:209], v128 offset:4096
	ds_read_b128 v[214:217], v128 offset:4352
	ds_read_b128 v[222:225], v128 offset:4608
	ds_read_b128 v[230:233], v128 offset:4864
	ds_read_b32 v130, v129 offset:4360
	ds_read_b32 v131, v129 offset:4616
	ds_read_b32 v132, v129 offset:4648
	ds_read_b32 v133, v129 offset:4872
	ds_read_b32 v134, v129 offset:4904
	ds_read_b32 v135, v129 offset:4936
	v_add_f32_dpp v112, v112, v112 quad_perm:[1,0,3,2] row_mask:0xf bank_mask:0xf bound_ctrl:1
	v_add_f32_dpp v113, v113, v113 quad_perm:[1,0,3,2] row_mask:0xf bank_mask:0xf bound_ctrl:1
	v_cmp_eq_u32_e32 vcc, 16, v0
	v_add_f32_dpp v114, v114, v114 quad_perm:[1,0,3,2] row_mask:0xf bank_mask:0xf bound_ctrl:1
	v_add_f32_dpp v115, v115, v115 quad_perm:[1,0,3,2] row_mask:0xf bank_mask:0xf bound_ctrl:1
	v_cndmask_b32_e64 v116, 0, 1.0, vcc
	v_cmp_eq_u32_e32 vcc, 17, v0
	v_add_f32_dpp v112, v112, v112 quad_perm:[2,3,0,1] row_mask:0xf bank_mask:0xf bound_ctrl:1
	v_add_f32_dpp v113, v113, v113 quad_perm:[2,3,0,1] row_mask:0xf bank_mask:0xf bound_ctrl:1
	v_cndmask_b32_e64 v117, 0, 1.0, vcc
	v_cmp_eq_u32_e32 vcc, 18, v0
	v_add_f32_dpp v114, v114, v114 quad_perm:[2,3,0,1] row_mask:0xf bank_mask:0xf bound_ctrl:1
	v_add_f32_dpp v115, v115, v115 quad_perm:[2,3,0,1] row_mask:0xf bank_mask:0xf bound_ctrl:1
	v_cndmask_b32_e64 v118, 0, 1.0, vcc
	v_cmp_eq_u32_e32 vcc, 19, v0
	v_add_f32_dpp v112, v112, v112 row_half_mirror row_mask:0xf bank_mask:0xf bound_ctrl:1
	v_add_f32_dpp v113, v113, v113 row_half_mirror row_mask:0xf bank_mask:0xf bound_ctrl:1
	v_cndmask_b32_e64 v119, 0, 1.0, vcc
	v_add_f32_dpp v114, v114, v114 row_half_mirror row_mask:0xf bank_mask:0xf bound_ctrl:1
	v_add_f32_dpp v115, v115, v115 row_half_mirror row_mask:0xf bank_mask:0xf bound_ctrl:1
	v_sub_f32_e32 v124, v120, v112
	v_sub_f32_e32 v125, v121, v113
	v_sub_f32_e32 v126, v122, v114
	v_sub_f32_e32 v127, v123, v115
	v_fma_f32 v125, -v146, v124, v125
	v_fma_f32 v126, -v147, v124, v126
	v_fma_f32 v127, -v149, v124, v127
	s_waitcnt lgkmcnt(9)
	v_mul_f32_e32 v108, v206, v100
	s_waitcnt lgkmcnt(8)
	v_mul_f32_e32 v109, v214, v100
	v_fma_f32 v126, -v148, v125, v126
	v_fma_f32 v127, -v150, v125, v127
	s_waitcnt lgkmcnt(7)
	v_mul_f32_e32 v110, v222, v100
	s_waitcnt lgkmcnt(6)
	v_mul_f32_e32 v111, v230, v100
	v_fma_f32 v127, -v151, v126, v127
	v_cndmask_b32_e64 v101, v101, v124, s[14:15]
	v_cndmask_b32_e64 v101, v101, v125, s[16:17]
	v_cndmask_b32_e64 v101, v101, v126, s[18:19]
	v_cndmask_b32_e64 v101, v101, v127, s[20:21]
	v_fmac_f32_e32 v108, v207, v101
	v_fmac_f32_e32 v109, v215, v101
	v_fmac_f32_e32 v110, v223, v101
	v_fmac_f32_e32 v111, v231, v101
	s_waitcnt lgkmcnt(0)
	ds_read_b128 v[176:179], v128 offset:5120
	ds_read_b128 v[184:187], v128 offset:5376
	ds_read_b128 v[192:195], v128 offset:5632
	ds_read_b128 v[200:203], v128 offset:5888
	ds_read_b32 v146, v129 offset:5512
	ds_read_b32 v147, v129 offset:5768
	ds_read_b32 v148, v129 offset:5800
	ds_read_b32 v149, v129 offset:6024
	ds_read_b32 v150, v129 offset:6056
	ds_read_b32 v151, v129 offset:6088
	v_add_f32_dpp v108, v108, v108 quad_perm:[1,0,3,2] row_mask:0xf bank_mask:0xf bound_ctrl:1
	v_add_f32_dpp v109, v109, v109 quad_perm:[1,0,3,2] row_mask:0xf bank_mask:0xf bound_ctrl:1
	v_cmp_eq_u32_e32 vcc, 20, v0
	v_add_f32_dpp v110, v110, v110 quad_perm:[1,0,3,2] row_mask:0xf bank_mask:0xf bound_ctrl:1
	v_add_f32_dpp v111, v111, v111 quad_perm:[1,0,3,2] row_mask:0xf bank_mask:0xf bound_ctrl:1
	v_cndmask_b32_e64 v120, 0, 1.0, vcc
	v_cmp_eq_u32_e32 vcc, 21, v0
	v_add_f32_dpp v108, v108, v108 quad_perm:[2,3,0,1] row_mask:0xf bank_mask:0xf bound_ctrl:1
	v_add_f32_dpp v109, v109, v109 quad_perm:[2,3,0,1] row_mask:0xf bank_mask:0xf bound_ctrl:1
	v_cndmask_b32_e64 v121, 0, 1.0, vcc
	v_cmp_eq_u32_e32 vcc, 22, v0
	v_add_f32_dpp v110, v110, v110 quad_perm:[2,3,0,1] row_mask:0xf bank_mask:0xf bound_ctrl:1
	v_add_f32_dpp v111, v111, v111 quad_perm:[2,3,0,1] row_mask:0xf bank_mask:0xf bound_ctrl:1
	v_cndmask_b32_e64 v122, 0, 1.0, vcc
	v_cmp_eq_u32_e32 vcc, 23, v0
	v_add_f32_dpp v108, v108, v108 row_half_mirror row_mask:0xf bank_mask:0xf bound_ctrl:1
	v_add_f32_dpp v109, v109, v109 row_half_mirror row_mask:0xf bank_mask:0xf bound_ctrl:1
	v_cndmask_b32_e64 v123, 0, 1.0, vcc
	v_add_f32_dpp v110, v110, v110 row_half_mirror row_mask:0xf bank_mask:0xf bound_ctrl:1
	v_add_f32_dpp v111, v111, v111 row_half_mirror row_mask:0xf bank_mask:0xf bound_ctrl:1
	v_sub_f32_e32 v124, v116, v108
	v_sub_f32_e32 v125, v117, v109
	v_sub_f32_e32 v126, v118, v110
	v_sub_f32_e32 v127, v119, v111
	v_fma_f32 v125, -v130, v124, v125
	v_fma_f32 v126, -v131, v124, v126
	v_fma_f32 v127, -v133, v124, v127
	s_waitcnt lgkmcnt(9)
	v_mul_f32_e32 v112, v176, v100
	s_waitcnt lgkmcnt(8)
	v_mul_f32_e32 v113, v184, v100
	v_fma_f32 v126, -v132, v125, v126
	v_fma_f32 v127, -v134, v125, v127
	s_waitcnt lgkmcnt(7)
	v_mul_f32_e32 v114, v192, v100
	s_waitcnt lgkmcnt(6)
	v_mul_f32_e32 v115, v200, v100
	v_fma_f32 v127, -v135, v126, v127
	v_fmac_f32_e32 v112, v177, v101
	v_fmac_f32_e32 v113, v185, v101
	v_cndmask_b32_e64 v102, v102, v124, s[6:7]
	v_fmac_f32_e32 v114, v193, v101
	v_cndmask_b32_e64 v102, v102, v125, s[8:9]
	v_fmac_f32_e32 v115, v201, v101
	v_cndmask_b32_e64 v102, v102, v126, s[10:11]
	v_cndmask_b32_e64 v102, v102, v127, s[12:13]
	v_fmac_f32_e32 v112, v178, v102
	v_fmac_f32_e32 v113, v186, v102
	v_fmac_f32_e32 v114, v194, v102
	v_fmac_f32_e32 v115, v202, v102
	s_waitcnt lgkmcnt(0)
	ds_read_b128 v[206:209], v128 offset:6144
	ds_read_b128 v[214:217], v128 offset:6400
	ds_read_b128 v[222:225], v128 offset:6656
	ds_read_b128 v[230:233], v128 offset:6912
	ds_read_b32 v130, v129 offset:6412
	ds_read_b32 v131, v129 offset:6668
	ds_read_b32 v132, v129 offset:6700
	ds_read_b32 v133, v129 offset:6924
	ds_read_b32 v134, v129 offset:6956
	ds_read_b32 v135, v129 offset:6988
	v_add_f32_dpp v112, v112, v112 quad_perm:[1,0,3,2] row_mask:0xf bank_mask:0xf bound_ctrl:1
	v_add_f32_dpp v113, v113, v113 quad_perm:[1,0,3,2] row_mask:0xf bank_mask:0xf bound_ctrl:1
	v_cmp_eq_u32_e32 vcc, 24, v0
	v_add_f32_dpp v114, v114, v114 quad_perm:[1,0,3,2] row_mask:0xf bank_mask:0xf bound_ctrl:1
	v_add_f32_dpp v115, v115, v115 quad_perm:[1,0,3,2] row_mask:0xf bank_mask:0xf bound_ctrl:1
	v_cndmask_b32_e64 v116, 0, 1.0, vcc
	v_cmp_eq_u32_e32 vcc, 25, v0
	v_add_f32_dpp v112, v112, v112 quad_perm:[2,3,0,1] row_mask:0xf bank_mask:0xf bound_ctrl:1
	v_add_f32_dpp v113, v113, v113 quad_perm:[2,3,0,1] row_mask:0xf bank_mask:0xf bound_ctrl:1
	v_cndmask_b32_e64 v117, 0, 1.0, vcc
	v_cmp_eq_u32_e32 vcc, 26, v0
	v_add_f32_dpp v114, v114, v114 quad_perm:[2,3,0,1] row_mask:0xf bank_mask:0xf bound_ctrl:1
	v_add_f32_dpp v115, v115, v115 quad_perm:[2,3,0,1] row_mask:0xf bank_mask:0xf bound_ctrl:1
	v_cndmask_b32_e64 v118, 0, 1.0, vcc
	v_cmp_eq_u32_e32 vcc, 27, v0
	v_add_f32_dpp v112, v112, v112 row_half_mirror row_mask:0xf bank_mask:0xf bound_ctrl:1
	v_add_f32_dpp v113, v113, v113 row_half_mirror row_mask:0xf bank_mask:0xf bound_ctrl:1
	v_cndmask_b32_e64 v119, 0, 1.0, vcc
	v_add_f32_dpp v114, v114, v114 row_half_mirror row_mask:0xf bank_mask:0xf bound_ctrl:1
	v_add_f32_dpp v115, v115, v115 row_half_mirror row_mask:0xf bank_mask:0xf bound_ctrl:1
	v_sub_f32_e32 v124, v120, v112
	v_sub_f32_e32 v125, v121, v113
	v_sub_f32_e32 v126, v122, v114
	v_sub_f32_e32 v127, v123, v115
	v_fma_f32 v125, -v146, v124, v125
	v_fma_f32 v126, -v147, v124, v126
	v_fma_f32 v127, -v149, v124, v127
	s_waitcnt lgkmcnt(9)
	v_mul_f32_e32 v108, v206, v100
	s_waitcnt lgkmcnt(8)
	v_mul_f32_e32 v109, v214, v100
	v_fma_f32 v126, -v148, v125, v126
	v_fma_f32 v127, -v150, v125, v127
	s_waitcnt lgkmcnt(7)
	v_mul_f32_e32 v110, v222, v100
	s_waitcnt lgkmcnt(6)
	v_mul_f32_e32 v111, v230, v100
	v_fma_f32 v127, -v151, v126, v127
	v_fmac_f32_e32 v108, v207, v101
	v_fmac_f32_e32 v109, v215, v101
	v_cndmask_b32_e64 v102, v102, v124, s[14:15]
	v_fmac_f32_e32 v110, v223, v101
	v_cndmask_b32_e64 v102, v102, v125, s[16:17]
	v_fmac_f32_e32 v111, v231, v101
	v_cndmask_b32_e64 v102, v102, v126, s[18:19]
	v_cndmask_b32_e64 v102, v102, v127, s[20:21]
	v_fmac_f32_e32 v108, v208, v102
	v_fmac_f32_e32 v109, v216, v102
	v_fmac_f32_e32 v110, v224, v102
	v_fmac_f32_e32 v111, v232, v102
	s_waitcnt lgkmcnt(0)
	ds_read_b128 v[176:179], v128 offset:7168
	ds_read_b128 v[184:187], v128 offset:7424
	ds_read_b128 v[192:195], v128 offset:7680
	ds_read_b128 v[200:203], v128 offset:7936
	ds_read_b32 v146, v129 offset:7564
	ds_read_b32 v147, v129 offset:7820
	ds_read_b32 v148, v129 offset:7852
	ds_read_b32 v149, v129 offset:8076
	ds_read_b32 v150, v129 offset:8108
	ds_read_b32 v151, v129 offset:8140
	v_add_f32_dpp v108, v108, v108 quad_perm:[1,0,3,2] row_mask:0xf bank_mask:0xf bound_ctrl:1
	v_add_f32_dpp v109, v109, v109 quad_perm:[1,0,3,2] row_mask:0xf bank_mask:0xf bound_ctrl:1
	v_cmp_eq_u32_e32 vcc, 28, v0
	v_add_f32_dpp v110, v110, v110 quad_perm:[1,0,3,2] row_mask:0xf bank_mask:0xf bound_ctrl:1
	v_add_f32_dpp v111, v111, v111 quad_perm:[1,0,3,2] row_mask:0xf bank_mask:0xf bound_ctrl:1
	v_cndmask_b32_e64 v120, 0, 1.0, vcc
	v_cmp_eq_u32_e32 vcc, 29, v0
	v_add_f32_dpp v108, v108, v108 quad_perm:[2,3,0,1] row_mask:0xf bank_mask:0xf bound_ctrl:1
	v_add_f32_dpp v109, v109, v109 quad_perm:[2,3,0,1] row_mask:0xf bank_mask:0xf bound_ctrl:1
	v_cndmask_b32_e64 v121, 0, 1.0, vcc
	v_cmp_eq_u32_e32 vcc, 30, v0
	v_add_f32_dpp v110, v110, v110 quad_perm:[2,3,0,1] row_mask:0xf bank_mask:0xf bound_ctrl:1
	v_add_f32_dpp v111, v111, v111 quad_perm:[2,3,0,1] row_mask:0xf bank_mask:0xf bound_ctrl:1
	v_cndmask_b32_e64 v122, 0, 1.0, vcc
	v_cmp_eq_u32_e32 vcc, 31, v0
	v_add_f32_dpp v108, v108, v108 row_half_mirror row_mask:0xf bank_mask:0xf bound_ctrl:1
	v_add_f32_dpp v109, v109, v109 row_half_mirror row_mask:0xf bank_mask:0xf bound_ctrl:1
	v_cndmask_b32_e64 v123, 0, 1.0, vcc
	v_add_f32_dpp v110, v110, v110 row_half_mirror row_mask:0xf bank_mask:0xf bound_ctrl:1
	v_add_f32_dpp v111, v111, v111 row_half_mirror row_mask:0xf bank_mask:0xf bound_ctrl:1
	v_sub_f32_e32 v124, v116, v108
	v_sub_f32_e32 v125, v117, v109
	v_sub_f32_e32 v126, v118, v110
	v_sub_f32_e32 v127, v119, v111
	v_fma_f32 v125, -v130, v124, v125
	v_fma_f32 v126, -v131, v124, v126
	v_fma_f32 v127, -v133, v124, v127
	s_waitcnt lgkmcnt(9)
	v_mul_f32_e32 v112, v176, v100
	s_waitcnt lgkmcnt(8)
	v_mul_f32_e32 v113, v184, v100
	v_fma_f32 v126, -v132, v125, v126
	v_fma_f32 v127, -v134, v125, v127
	s_waitcnt lgkmcnt(7)
	v_mul_f32_e32 v114, v192, v100
	s_waitcnt lgkmcnt(6)
	v_mul_f32_e32 v115, v200, v100
	v_fma_f32 v127, -v135, v126, v127
	v_fmac_f32_e32 v112, v177, v101
	v_fmac_f32_e32 v113, v185, v101
	v_cndmask_b32_e64 v103, v103, v124, s[6:7]
	v_fmac_f32_e32 v114, v193, v101
	v_cndmask_b32_e64 v103, v103, v125, s[8:9]
	v_fmac_f32_e32 v115, v201, v101
	v_cndmask_b32_e64 v103, v103, v126, s[10:11]
	v_fmac_f32_e32 v112, v178, v102
	v_cndmask_b32_e64 v103, v103, v127, s[12:13]
	v_fmac_f32_e32 v113, v186, v102
	v_fmac_f32_e32 v114, v194, v102
	v_fmac_f32_e32 v115, v202, v102
	v_fmac_f32_e32 v112, v179, v103
	v_fmac_f32_e32 v113, v187, v103
	v_fmac_f32_e32 v114, v195, v103
	v_fmac_f32_e32 v115, v203, v103
	s_waitcnt lgkmcnt(0)
	ds_read_b128 v[206:209], v128 offset:8192
	ds_read_b128 v[214:217], v128 offset:8448
	ds_read_b128 v[222:225], v128 offset:8704
	ds_read_b128 v[230:233], v128 offset:8960
	ds_read_b32 v130, v129 offset:8464
	ds_read_b32 v131, v129 offset:8720
	ds_read_b32 v132, v129 offset:8752
	ds_read_b32 v133, v129 offset:8976
	ds_read_b32 v134, v129 offset:9008
	ds_read_b32 v135, v129 offset:9040
	v_add_f32_dpp v112, v112, v112 quad_perm:[1,0,3,2] row_mask:0xf bank_mask:0xf bound_ctrl:1
	v_add_f32_dpp v113, v113, v113 quad_perm:[1,0,3,2] row_mask:0xf bank_mask:0xf bound_ctrl:1
	v_cmp_eq_u32_e32 vcc, 32, v0
	v_add_f32_dpp v114, v114, v114 quad_perm:[1,0,3,2] row_mask:0xf bank_mask:0xf bound_ctrl:1
	v_add_f32_dpp v115, v115, v115 quad_perm:[1,0,3,2] row_mask:0xf bank_mask:0xf bound_ctrl:1
	v_cndmask_b32_e64 v116, 0, 1.0, vcc
	v_cmp_eq_u32_e32 vcc, 33, v0
	v_add_f32_dpp v112, v112, v112 quad_perm:[2,3,0,1] row_mask:0xf bank_mask:0xf bound_ctrl:1
	v_add_f32_dpp v113, v113, v113 quad_perm:[2,3,0,1] row_mask:0xf bank_mask:0xf bound_ctrl:1
	v_cndmask_b32_e64 v117, 0, 1.0, vcc
	v_cmp_eq_u32_e32 vcc, 34, v0
	v_add_f32_dpp v114, v114, v114 quad_perm:[2,3,0,1] row_mask:0xf bank_mask:0xf bound_ctrl:1
	v_add_f32_dpp v115, v115, v115 quad_perm:[2,3,0,1] row_mask:0xf bank_mask:0xf bound_ctrl:1
	v_cndmask_b32_e64 v118, 0, 1.0, vcc
	v_cmp_eq_u32_e32 vcc, 35, v0
	v_add_f32_dpp v112, v112, v112 row_half_mirror row_mask:0xf bank_mask:0xf bound_ctrl:1
	v_add_f32_dpp v113, v113, v113 row_half_mirror row_mask:0xf bank_mask:0xf bound_ctrl:1
	v_cndmask_b32_e64 v119, 0, 1.0, vcc
	v_add_f32_dpp v114, v114, v114 row_half_mirror row_mask:0xf bank_mask:0xf bound_ctrl:1
	v_add_f32_dpp v115, v115, v115 row_half_mirror row_mask:0xf bank_mask:0xf bound_ctrl:1
	v_sub_f32_e32 v124, v120, v112
	v_sub_f32_e32 v125, v121, v113
	v_sub_f32_e32 v126, v122, v114
	v_sub_f32_e32 v127, v123, v115
	v_fma_f32 v125, -v146, v124, v125
	v_fma_f32 v126, -v147, v124, v126
	v_fma_f32 v127, -v149, v124, v127
	s_waitcnt lgkmcnt(9)
	v_mul_f32_e32 v108, v206, v100
	s_waitcnt lgkmcnt(8)
	v_mul_f32_e32 v109, v214, v100
	v_fma_f32 v126, -v148, v125, v126
	v_fma_f32 v127, -v150, v125, v127
	s_waitcnt lgkmcnt(7)
	v_mul_f32_e32 v110, v222, v100
	s_waitcnt lgkmcnt(6)
	v_mul_f32_e32 v111, v230, v100
	v_fma_f32 v127, -v151, v126, v127
	v_fmac_f32_e32 v108, v207, v101
	v_fmac_f32_e32 v109, v215, v101
	v_cndmask_b32_e64 v103, v103, v124, s[14:15]
	v_fmac_f32_e32 v110, v223, v101
	v_cndmask_b32_e64 v103, v103, v125, s[16:17]
	v_fmac_f32_e32 v111, v231, v101
	v_cndmask_b32_e64 v103, v103, v126, s[18:19]
	v_fmac_f32_e32 v108, v208, v102
	v_cndmask_b32_e64 v103, v103, v127, s[20:21]
	v_fmac_f32_e32 v109, v216, v102
	v_fmac_f32_e32 v110, v224, v102
	v_fmac_f32_e32 v111, v232, v102
	v_fmac_f32_e32 v108, v209, v103
	v_fmac_f32_e32 v109, v217, v103
	v_fmac_f32_e32 v110, v225, v103
	v_fmac_f32_e32 v111, v233, v103
	s_waitcnt lgkmcnt(0)
	ds_read_b128 v[176:179], v128 offset:9216
	ds_read_b128 v[180:183], v128 offset:9232
	ds_read_b128 v[184:187], v128 offset:9472
	ds_read_b128 v[188:191], v128 offset:9488
	ds_read_b128 v[192:195], v128 offset:9728
	ds_read_b128 v[196:199], v128 offset:9744
	ds_read_b128 v[200:203], v128 offset:9984
	ds_read_b128 v[238:241], v128 offset:10000
	ds_read_b32 v146, v129 offset:9616
	ds_read_b32 v147, v129 offset:9872
	ds_read_b32 v148, v129 offset:9904
	ds_read_b32 v149, v129 offset:10128
	ds_read_b32 v150, v129 offset:10160
	ds_read_b32 v151, v129 offset:10192
	v_add_f32_dpp v108, v108, v108 quad_perm:[1,0,3,2] row_mask:0xf bank_mask:0xf bound_ctrl:1
	v_add_f32_dpp v109, v109, v109 quad_perm:[1,0,3,2] row_mask:0xf bank_mask:0xf bound_ctrl:1
	v_cmp_eq_u32_e32 vcc, 36, v0
	v_add_f32_dpp v110, v110, v110 quad_perm:[1,0,3,2] row_mask:0xf bank_mask:0xf bound_ctrl:1
	v_add_f32_dpp v111, v111, v111 quad_perm:[1,0,3,2] row_mask:0xf bank_mask:0xf bound_ctrl:1
	v_cndmask_b32_e64 v120, 0, 1.0, vcc
	v_cmp_eq_u32_e32 vcc, 37, v0
	v_add_f32_dpp v108, v108, v108 quad_perm:[2,3,0,1] row_mask:0xf bank_mask:0xf bound_ctrl:1
	v_add_f32_dpp v109, v109, v109 quad_perm:[2,3,0,1] row_mask:0xf bank_mask:0xf bound_ctrl:1
	v_cndmask_b32_e64 v121, 0, 1.0, vcc
	v_cmp_eq_u32_e32 vcc, 38, v0
	v_add_f32_dpp v110, v110, v110 quad_perm:[2,3,0,1] row_mask:0xf bank_mask:0xf bound_ctrl:1
	v_add_f32_dpp v111, v111, v111 quad_perm:[2,3,0,1] row_mask:0xf bank_mask:0xf bound_ctrl:1
	v_cndmask_b32_e64 v122, 0, 1.0, vcc
	v_cmp_eq_u32_e32 vcc, 39, v0
	v_add_f32_dpp v108, v108, v108 row_half_mirror row_mask:0xf bank_mask:0xf bound_ctrl:1
	v_add_f32_dpp v109, v109, v109 row_half_mirror row_mask:0xf bank_mask:0xf bound_ctrl:1
	v_cndmask_b32_e64 v123, 0, 1.0, vcc
	v_add_f32_dpp v110, v110, v110 row_half_mirror row_mask:0xf bank_mask:0xf bound_ctrl:1
	v_add_f32_dpp v111, v111, v111 row_half_mirror row_mask:0xf bank_mask:0xf bound_ctrl:1
	v_sub_f32_e32 v124, v116, v108
	v_sub_f32_e32 v125, v117, v109
	v_sub_f32_e32 v126, v118, v110
	v_sub_f32_e32 v127, v119, v111
	v_fma_f32 v125, -v130, v124, v125
	v_fma_f32 v126, -v131, v124, v126
	v_fma_f32 v127, -v133, v124, v127
	s_waitcnt lgkmcnt(13)
	v_mul_f32_e32 v112, v176, v100
	s_waitcnt lgkmcnt(11)
	v_mul_f32_e32 v113, v184, v100
	v_fma_f32 v126, -v132, v125, v126
	v_fma_f32 v127, -v134, v125, v127
	s_waitcnt lgkmcnt(9)
	v_mul_f32_e32 v114, v192, v100
	s_waitcnt lgkmcnt(7)
	v_mul_f32_e32 v115, v200, v100
	v_fma_f32 v127, -v135, v126, v127
	v_fmac_f32_e32 v112, v177, v101
	v_fmac_f32_e32 v113, v185, v101
	v_cndmask_b32_e64 v104, v104, v124, s[6:7]
	v_fmac_f32_e32 v114, v193, v101
	v_cndmask_b32_e64 v104, v104, v125, s[8:9]
	v_fmac_f32_e32 v115, v201, v101
	v_cndmask_b32_e64 v104, v104, v126, s[10:11]
	v_fmac_f32_e32 v112, v178, v102
	v_cndmask_b32_e64 v104, v104, v127, s[12:13]
	v_fmac_f32_e32 v113, v186, v102
	v_fmac_f32_e32 v114, v194, v102
	v_fmac_f32_e32 v115, v202, v102
	v_fmac_f32_e32 v112, v179, v103
	v_fmac_f32_e32 v113, v187, v103
	v_fmac_f32_e32 v114, v195, v103
	v_fmac_f32_e32 v115, v203, v103
	v_fmac_f32_e32 v112, v180, v104
	v_fmac_f32_e32 v113, v188, v104
	v_fmac_f32_e32 v114, v196, v104
	s_waitcnt lgkmcnt(6)
	v_fmac_f32_e32 v115, v238, v104
	s_waitcnt lgkmcnt(0)
	ds_read_b128 v[206:209], v128 offset:10240
	ds_read_b128 v[210:213], v128 offset:10256
	ds_read_b128 v[214:217], v128 offset:10496
	ds_read_b128 v[218:221], v128 offset:10512
	ds_read_b128 v[222:225], v128 offset:10752
	ds_read_b128 v[226:229], v128 offset:10768
	ds_read_b128 v[230:233], v128 offset:11008
	ds_read_b128 v[234:237], v128 offset:11024
	ds_read_b32 v130, v129 offset:10516
	ds_read_b32 v131, v129 offset:10772
	ds_read_b32 v132, v129 offset:10804
	ds_read_b32 v133, v129 offset:11028
	ds_read_b32 v134, v129 offset:11060
	ds_read_b32 v135, v129 offset:11092
	v_add_f32_dpp v112, v112, v112 quad_perm:[1,0,3,2] row_mask:0xf bank_mask:0xf bound_ctrl:1
	v_add_f32_dpp v113, v113, v113 quad_perm:[1,0,3,2] row_mask:0xf bank_mask:0xf bound_ctrl:1
	v_cmp_eq_u32_e32 vcc, 40, v0
	v_add_f32_dpp v114, v114, v114 quad_perm:[1,0,3,2] row_mask:0xf bank_mask:0xf bound_ctrl:1
	v_add_f32_dpp v115, v115, v115 quad_perm:[1,0,3,2] row_mask:0xf bank_mask:0xf bound_ctrl:1
	v_cndmask_b32_e64 v116, 0, 1.0, vcc
	v_cmp_eq_u32_e32 vcc, 41, v0
	v_add_f32_dpp v112, v112, v112 quad_perm:[2,3,0,1] row_mask:0xf bank_mask:0xf bound_ctrl:1
	v_add_f32_dpp v113, v113, v113 quad_perm:[2,3,0,1] row_mask:0xf bank_mask:0xf bound_ctrl:1
	v_cndmask_b32_e64 v117, 0, 1.0, vcc
	v_cmp_eq_u32_e32 vcc, 42, v0
	v_add_f32_dpp v114, v114, v114 quad_perm:[2,3,0,1] row_mask:0xf bank_mask:0xf bound_ctrl:1
	v_add_f32_dpp v115, v115, v115 quad_perm:[2,3,0,1] row_mask:0xf bank_mask:0xf bound_ctrl:1
	v_cndmask_b32_e64 v118, 0, 1.0, vcc
	v_cmp_eq_u32_e32 vcc, 43, v0
	v_add_f32_dpp v112, v112, v112 row_half_mirror row_mask:0xf bank_mask:0xf bound_ctrl:1
	v_add_f32_dpp v113, v113, v113 row_half_mirror row_mask:0xf bank_mask:0xf bound_ctrl:1
	v_cndmask_b32_e64 v119, 0, 1.0, vcc
	v_add_f32_dpp v114, v114, v114 row_half_mirror row_mask:0xf bank_mask:0xf bound_ctrl:1
	v_add_f32_dpp v115, v115, v115 row_half_mirror row_mask:0xf bank_mask:0xf bound_ctrl:1
	v_sub_f32_e32 v124, v120, v112
	v_sub_f32_e32 v125, v121, v113
	v_sub_f32_e32 v126, v122, v114
	v_sub_f32_e32 v127, v123, v115
	v_fma_f32 v125, -v146, v124, v125
	v_fma_f32 v126, -v147, v124, v126
	v_fma_f32 v127, -v149, v124, v127
	s_waitcnt lgkmcnt(13)
	v_mul_f32_e32 v108, v206, v100
	s_waitcnt lgkmcnt(11)
	v_mul_f32_e32 v109, v214, v100
	v_fma_f32 v126, -v148, v125, v126
	v_fma_f32 v127, -v150, v125, v127
	s_waitcnt lgkmcnt(9)
	v_mul_f32_e32 v110, v222, v100
	s_waitcnt lgkmcnt(7)
	v_mul_f32_e32 v111, v230, v100
	v_fma_f32 v127, -v151, v126, v127
	v_fmac_f32_e32 v108, v207, v101
	v_fmac_f32_e32 v109, v215, v101
	v_cndmask_b32_e64 v104, v104, v124, s[14:15]
	v_fmac_f32_e32 v110, v223, v101
	v_cndmask_b32_e64 v104, v104, v125, s[16:17]
	v_fmac_f32_e32 v111, v231, v101
	v_cndmask_b32_e64 v104, v104, v126, s[18:19]
	v_fmac_f32_e32 v108, v208, v102
	v_cndmask_b32_e64 v104, v104, v127, s[20:21]
	v_fmac_f32_e32 v109, v216, v102
	v_fmac_f32_e32 v110, v224, v102
	v_fmac_f32_e32 v111, v232, v102
	v_fmac_f32_e32 v108, v209, v103
	v_fmac_f32_e32 v109, v217, v103
	v_fmac_f32_e32 v110, v225, v103
	v_fmac_f32_e32 v111, v233, v103
	v_fmac_f32_e32 v108, v210, v104
	v_fmac_f32_e32 v109, v218, v104
	v_fmac_f32_e32 v110, v226, v104
	s_waitcnt lgkmcnt(6)
	v_fmac_f32_e32 v111, v234, v104
	s_waitcnt lgkmcnt(0)
	ds_read_b128 v[176:179], v128 offset:11264
	ds_read_b128 v[180:183], v128 offset:11280
	ds_read_b128 v[184:187], v128 offset:11520
	ds_read_b128 v[188:191], v128 offset:11536
	ds_read_b128 v[192:195], v128 offset:11776
	ds_read_b128 v[196:199], v128 offset:11792
	ds_read_b128 v[200:203], v128 offset:12032
	ds_read_b128 v[238:241], v128 offset:12048
	ds_read_b32 v146, v129 offset:11668
	ds_read_b32 v147, v129 offset:11924
	ds_read_b32 v148, v129 offset:11956
	ds_read_b32 v149, v129 offset:12180
	ds_read_b32 v150, v129 offset:12212
	ds_read_b32 v151, v129 offset:12244
	v_add_f32_dpp v108, v108, v108 quad_perm:[1,0,3,2] row_mask:0xf bank_mask:0xf bound_ctrl:1
	v_add_f32_dpp v109, v109, v109 quad_perm:[1,0,3,2] row_mask:0xf bank_mask:0xf bound_ctrl:1
	v_cmp_eq_u32_e32 vcc, 44, v0
	v_add_f32_dpp v110, v110, v110 quad_perm:[1,0,3,2] row_mask:0xf bank_mask:0xf bound_ctrl:1
	v_add_f32_dpp v111, v111, v111 quad_perm:[1,0,3,2] row_mask:0xf bank_mask:0xf bound_ctrl:1
	v_cndmask_b32_e64 v120, 0, 1.0, vcc
	v_cmp_eq_u32_e32 vcc, 45, v0
	v_add_f32_dpp v108, v108, v108 quad_perm:[2,3,0,1] row_mask:0xf bank_mask:0xf bound_ctrl:1
	v_add_f32_dpp v109, v109, v109 quad_perm:[2,3,0,1] row_mask:0xf bank_mask:0xf bound_ctrl:1
	v_cndmask_b32_e64 v121, 0, 1.0, vcc
	v_cmp_eq_u32_e32 vcc, 46, v0
	v_add_f32_dpp v110, v110, v110 quad_perm:[2,3,0,1] row_mask:0xf bank_mask:0xf bound_ctrl:1
	v_add_f32_dpp v111, v111, v111 quad_perm:[2,3,0,1] row_mask:0xf bank_mask:0xf bound_ctrl:1
	v_cndmask_b32_e64 v122, 0, 1.0, vcc
	v_cmp_eq_u32_e32 vcc, 47, v0
	v_add_f32_dpp v108, v108, v108 row_half_mirror row_mask:0xf bank_mask:0xf bound_ctrl:1
	v_add_f32_dpp v109, v109, v109 row_half_mirror row_mask:0xf bank_mask:0xf bound_ctrl:1
	v_cndmask_b32_e64 v123, 0, 1.0, vcc
	v_add_f32_dpp v110, v110, v110 row_half_mirror row_mask:0xf bank_mask:0xf bound_ctrl:1
	v_add_f32_dpp v111, v111, v111 row_half_mirror row_mask:0xf bank_mask:0xf bound_ctrl:1
	v_sub_f32_e32 v124, v116, v108
	v_sub_f32_e32 v125, v117, v109
	v_sub_f32_e32 v126, v118, v110
	v_sub_f32_e32 v127, v119, v111
	v_fma_f32 v125, -v130, v124, v125
	v_fma_f32 v126, -v131, v124, v126
	v_fma_f32 v127, -v133, v124, v127
	s_waitcnt lgkmcnt(13)
	v_mul_f32_e32 v112, v176, v100
	s_waitcnt lgkmcnt(11)
	v_mul_f32_e32 v113, v184, v100
	v_fma_f32 v126, -v132, v125, v126
	v_fma_f32 v127, -v134, v125, v127
	s_waitcnt lgkmcnt(9)
	v_mul_f32_e32 v114, v192, v100
	s_waitcnt lgkmcnt(7)
	v_mul_f32_e32 v115, v200, v100
	v_fma_f32 v127, -v135, v126, v127
	v_fmac_f32_e32 v112, v177, v101
	v_fmac_f32_e32 v113, v185, v101
	v_cndmask_b32_e64 v105, v105, v124, s[6:7]
	v_fmac_f32_e32 v114, v193, v101
	v_cndmask_b32_e64 v105, v105, v125, s[8:9]
	v_fmac_f32_e32 v115, v201, v101
	v_cndmask_b32_e64 v105, v105, v126, s[10:11]
	v_fmac_f32_e32 v112, v178, v102
	v_cndmask_b32_e64 v105, v105, v127, s[12:13]
	v_fmac_f32_e32 v113, v186, v102
	v_fmac_f32_e32 v114, v194, v102
	v_fmac_f32_e32 v115, v202, v102
	v_fmac_f32_e32 v112, v179, v103
	v_fmac_f32_e32 v113, v187, v103
	v_fmac_f32_e32 v114, v195, v103
	v_fmac_f32_e32 v115, v203, v103
	v_fmac_f32_e32 v112, v180, v104
	v_fmac_f32_e32 v113, v188, v104
	v_fmac_f32_e32 v114, v196, v104
	s_waitcnt lgkmcnt(6)
	v_fmac_f32_e32 v115, v238, v104
	v_fmac_f32_e32 v112, v181, v105
	v_fmac_f32_e32 v113, v189, v105
	v_fmac_f32_e32 v114, v197, v105
	v_fmac_f32_e32 v115, v239, v105
	s_waitcnt lgkmcnt(0)
	ds_read_b128 v[206:209], v128 offset:12288
	ds_read_b128 v[210:213], v128 offset:12304
	ds_read_b128 v[214:217], v128 offset:12544
	ds_read_b128 v[218:221], v128 offset:12560
	ds_read_b128 v[222:225], v128 offset:12800
	ds_read_b128 v[226:229], v128 offset:12816
	ds_read_b128 v[230:233], v128 offset:13056
	ds_read_b128 v[234:237], v128 offset:13072
	ds_read_b32 v130, v129 offset:12568
	ds_read_b32 v131, v129 offset:12824
	ds_read_b32 v132, v129 offset:12856
	ds_read_b32 v133, v129 offset:13080
	ds_read_b32 v134, v129 offset:13112
	ds_read_b32 v135, v129 offset:13144
	v_add_f32_dpp v112, v112, v112 quad_perm:[1,0,3,2] row_mask:0xf bank_mask:0xf bound_ctrl:1
	v_add_f32_dpp v113, v113, v113 quad_perm:[1,0,3,2] row_mask:0xf bank_mask:0xf bound_ctrl:1
	v_cmp_eq_u32_e32 vcc, 48, v0
	v_add_f32_dpp v114, v114, v114 quad_perm:[1,0,3,2] row_mask:0xf bank_mask:0xf bound_ctrl:1
	v_add_f32_dpp v115, v115, v115 quad_perm:[1,0,3,2] row_mask:0xf bank_mask:0xf bound_ctrl:1
	v_cndmask_b32_e64 v116, 0, 1.0, vcc
	v_cmp_eq_u32_e32 vcc, 49, v0
	v_add_f32_dpp v112, v112, v112 quad_perm:[2,3,0,1] row_mask:0xf bank_mask:0xf bound_ctrl:1
	v_add_f32_dpp v113, v113, v113 quad_perm:[2,3,0,1] row_mask:0xf bank_mask:0xf bound_ctrl:1
	v_cndmask_b32_e64 v117, 0, 1.0, vcc
	v_cmp_eq_u32_e32 vcc, 50, v0
	v_add_f32_dpp v114, v114, v114 quad_perm:[2,3,0,1] row_mask:0xf bank_mask:0xf bound_ctrl:1
	v_add_f32_dpp v115, v115, v115 quad_perm:[2,3,0,1] row_mask:0xf bank_mask:0xf bound_ctrl:1
	v_cndmask_b32_e64 v118, 0, 1.0, vcc
	v_cmp_eq_u32_e32 vcc, 51, v0
	v_add_f32_dpp v112, v112, v112 row_half_mirror row_mask:0xf bank_mask:0xf bound_ctrl:1
	v_add_f32_dpp v113, v113, v113 row_half_mirror row_mask:0xf bank_mask:0xf bound_ctrl:1
	v_cndmask_b32_e64 v119, 0, 1.0, vcc
	v_add_f32_dpp v114, v114, v114 row_half_mirror row_mask:0xf bank_mask:0xf bound_ctrl:1
	v_add_f32_dpp v115, v115, v115 row_half_mirror row_mask:0xf bank_mask:0xf bound_ctrl:1
	v_sub_f32_e32 v124, v120, v112
	v_sub_f32_e32 v125, v121, v113
	v_sub_f32_e32 v126, v122, v114
	v_sub_f32_e32 v127, v123, v115
	v_fma_f32 v125, -v146, v124, v125
	v_fma_f32 v126, -v147, v124, v126
	v_fma_f32 v127, -v149, v124, v127
	s_waitcnt lgkmcnt(13)
	v_mul_f32_e32 v108, v206, v100
	s_waitcnt lgkmcnt(11)
	v_mul_f32_e32 v109, v214, v100
	v_fma_f32 v126, -v148, v125, v126
	v_fma_f32 v127, -v150, v125, v127
	s_waitcnt lgkmcnt(9)
	v_mul_f32_e32 v110, v222, v100
	s_waitcnt lgkmcnt(7)
	v_mul_f32_e32 v111, v230, v100
	v_fma_f32 v127, -v151, v126, v127
	v_fmac_f32_e32 v108, v207, v101
	v_fmac_f32_e32 v109, v215, v101
	v_cndmask_b32_e64 v105, v105, v124, s[14:15]
	v_fmac_f32_e32 v110, v223, v101
	v_cndmask_b32_e64 v105, v105, v125, s[16:17]
	v_fmac_f32_e32 v111, v231, v101
	v_cndmask_b32_e64 v105, v105, v126, s[18:19]
	v_fmac_f32_e32 v108, v208, v102
	v_cndmask_b32_e64 v105, v105, v127, s[20:21]
	v_fmac_f32_e32 v109, v216, v102
	v_fmac_f32_e32 v110, v224, v102
	v_fmac_f32_e32 v111, v232, v102
	v_fmac_f32_e32 v108, v209, v103
	v_fmac_f32_e32 v109, v217, v103
	v_fmac_f32_e32 v110, v225, v103
	v_fmac_f32_e32 v111, v233, v103
	v_fmac_f32_e32 v108, v210, v104
	v_fmac_f32_e32 v109, v218, v104
	v_fmac_f32_e32 v110, v226, v104
	s_waitcnt lgkmcnt(6)
	v_fmac_f32_e32 v111, v234, v104
	v_fmac_f32_e32 v108, v211, v105
	v_fmac_f32_e32 v109, v219, v105
	v_fmac_f32_e32 v110, v227, v105
	v_fmac_f32_e32 v111, v235, v105
	s_waitcnt lgkmcnt(0)
	ds_read_b128 v[176:179], v128 offset:13312
	ds_read_b128 v[180:183], v128 offset:13328
	ds_read_b128 v[184:187], v128 offset:13568
	ds_read_b128 v[188:191], v128 offset:13584
	ds_read_b128 v[192:195], v128 offset:13824
	ds_read_b128 v[196:199], v128 offset:13840
	ds_read_b128 v[200:203], v128 offset:14080
	ds_read_b128 v[238:241], v128 offset:14096
	ds_read_b32 v146, v129 offset:13720
	ds_read_b32 v147, v129 offset:13976
	ds_read_b32 v148, v129 offset:14008
	ds_read_b32 v149, v129 offset:14232
	ds_read_b32 v150, v129 offset:14264
	ds_read_b32 v151, v129 offset:14296
	v_add_f32_dpp v108, v108, v108 quad_perm:[1,0,3,2] row_mask:0xf bank_mask:0xf bound_ctrl:1
	v_add_f32_dpp v109, v109, v109 quad_perm:[1,0,3,2] row_mask:0xf bank_mask:0xf bound_ctrl:1
	v_cmp_eq_u32_e32 vcc, 52, v0
	v_add_f32_dpp v110, v110, v110 quad_perm:[1,0,3,2] row_mask:0xf bank_mask:0xf bound_ctrl:1
	v_add_f32_dpp v111, v111, v111 quad_perm:[1,0,3,2] row_mask:0xf bank_mask:0xf bound_ctrl:1
	v_cndmask_b32_e64 v120, 0, 1.0, vcc
	v_cmp_eq_u32_e32 vcc, 53, v0
	v_add_f32_dpp v108, v108, v108 quad_perm:[2,3,0,1] row_mask:0xf bank_mask:0xf bound_ctrl:1
	v_add_f32_dpp v109, v109, v109 quad_perm:[2,3,0,1] row_mask:0xf bank_mask:0xf bound_ctrl:1
	v_cndmask_b32_e64 v121, 0, 1.0, vcc
	v_cmp_eq_u32_e32 vcc, 54, v0
	v_add_f32_dpp v110, v110, v110 quad_perm:[2,3,0,1] row_mask:0xf bank_mask:0xf bound_ctrl:1
	v_add_f32_dpp v111, v111, v111 quad_perm:[2,3,0,1] row_mask:0xf bank_mask:0xf bound_ctrl:1
	v_cndmask_b32_e64 v122, 0, 1.0, vcc
	v_cmp_eq_u32_e32 vcc, 55, v0
	v_add_f32_dpp v108, v108, v108 row_half_mirror row_mask:0xf bank_mask:0xf bound_ctrl:1
	v_add_f32_dpp v109, v109, v109 row_half_mirror row_mask:0xf bank_mask:0xf bound_ctrl:1
	v_cndmask_b32_e64 v123, 0, 1.0, vcc
	v_add_f32_dpp v110, v110, v110 row_half_mirror row_mask:0xf bank_mask:0xf bound_ctrl:1
	v_add_f32_dpp v111, v111, v111 row_half_mirror row_mask:0xf bank_mask:0xf bound_ctrl:1
	v_sub_f32_e32 v124, v116, v108
	v_sub_f32_e32 v125, v117, v109
	v_sub_f32_e32 v126, v118, v110
	v_sub_f32_e32 v127, v119, v111
	v_fma_f32 v125, -v130, v124, v125
	v_fma_f32 v126, -v131, v124, v126
	v_fma_f32 v127, -v133, v124, v127
	s_waitcnt lgkmcnt(13)
	v_mul_f32_e32 v112, v176, v100
	s_waitcnt lgkmcnt(11)
	v_mul_f32_e32 v113, v184, v100
	v_fma_f32 v126, -v132, v125, v126
	v_fma_f32 v127, -v134, v125, v127
	s_waitcnt lgkmcnt(9)
	v_mul_f32_e32 v114, v192, v100
	s_waitcnt lgkmcnt(7)
	v_mul_f32_e32 v115, v200, v100
	v_fma_f32 v127, -v135, v126, v127
	v_fmac_f32_e32 v112, v177, v101
	v_fmac_f32_e32 v113, v185, v101
	v_cndmask_b32_e64 v106, v106, v124, s[6:7]
	v_fmac_f32_e32 v114, v193, v101
	v_cndmask_b32_e64 v106, v106, v125, s[8:9]
	v_fmac_f32_e32 v115, v201, v101
	v_cndmask_b32_e64 v106, v106, v126, s[10:11]
	v_fmac_f32_e32 v112, v178, v102
	v_cndmask_b32_e64 v106, v106, v127, s[12:13]
	v_fmac_f32_e32 v113, v186, v102
	v_fmac_f32_e32 v114, v194, v102
	v_fmac_f32_e32 v115, v202, v102
	v_fmac_f32_e32 v112, v179, v103
	v_fmac_f32_e32 v113, v187, v103
	v_fmac_f32_e32 v114, v195, v103
	v_fmac_f32_e32 v115, v203, v103
	v_fmac_f32_e32 v112, v180, v104
	v_fmac_f32_e32 v113, v188, v104
	v_fmac_f32_e32 v114, v196, v104
	s_waitcnt lgkmcnt(6)
	v_fmac_f32_e32 v115, v238, v104
	v_fmac_f32_e32 v112, v181, v105
	v_fmac_f32_e32 v113, v189, v105
	v_fmac_f32_e32 v114, v197, v105
	v_fmac_f32_e32 v115, v239, v105
	v_fmac_f32_e32 v112, v182, v106
	v_fmac_f32_e32 v113, v190, v106
	v_fmac_f32_e32 v114, v198, v106
	v_fmac_f32_e32 v115, v240, v106
	s_waitcnt lgkmcnt(0)
	ds_read_b128 v[206:209], v128 offset:14336
	ds_read_b128 v[210:213], v128 offset:14352
	ds_read_b128 v[214:217], v128 offset:14592
	ds_read_b128 v[218:221], v128 offset:14608
	ds_read_b128 v[222:225], v128 offset:14848
	ds_read_b128 v[226:229], v128 offset:14864
	ds_read_b128 v[230:233], v128 offset:15104
	ds_read_b128 v[234:237], v128 offset:15120
	ds_read_b32 v130, v129 offset:14620
	ds_read_b32 v131, v129 offset:14876
	ds_read_b32 v132, v129 offset:14908
	ds_read_b32 v133, v129 offset:15132
	ds_read_b32 v134, v129 offset:15164
	ds_read_b32 v135, v129 offset:15196
	v_add_f32_dpp v112, v112, v112 quad_perm:[1,0,3,2] row_mask:0xf bank_mask:0xf bound_ctrl:1
	v_add_f32_dpp v113, v113, v113 quad_perm:[1,0,3,2] row_mask:0xf bank_mask:0xf bound_ctrl:1
	v_cmp_eq_u32_e32 vcc, 56, v0
	v_add_f32_dpp v114, v114, v114 quad_perm:[1,0,3,2] row_mask:0xf bank_mask:0xf bound_ctrl:1
	v_add_f32_dpp v115, v115, v115 quad_perm:[1,0,3,2] row_mask:0xf bank_mask:0xf bound_ctrl:1
	v_cndmask_b32_e64 v116, 0, 1.0, vcc
	v_cmp_eq_u32_e32 vcc, 57, v0
	v_add_f32_dpp v112, v112, v112 quad_perm:[2,3,0,1] row_mask:0xf bank_mask:0xf bound_ctrl:1
	v_add_f32_dpp v113, v113, v113 quad_perm:[2,3,0,1] row_mask:0xf bank_mask:0xf bound_ctrl:1
	v_cndmask_b32_e64 v117, 0, 1.0, vcc
	v_cmp_eq_u32_e32 vcc, 58, v0
	v_add_f32_dpp v114, v114, v114 quad_perm:[2,3,0,1] row_mask:0xf bank_mask:0xf bound_ctrl:1
	v_add_f32_dpp v115, v115, v115 quad_perm:[2,3,0,1] row_mask:0xf bank_mask:0xf bound_ctrl:1
	v_cndmask_b32_e64 v118, 0, 1.0, vcc
	v_cmp_eq_u32_e32 vcc, 59, v0
	v_add_f32_dpp v112, v112, v112 row_half_mirror row_mask:0xf bank_mask:0xf bound_ctrl:1
	v_add_f32_dpp v113, v113, v113 row_half_mirror row_mask:0xf bank_mask:0xf bound_ctrl:1
	v_cndmask_b32_e64 v119, 0, 1.0, vcc
	v_add_f32_dpp v114, v114, v114 row_half_mirror row_mask:0xf bank_mask:0xf bound_ctrl:1
	v_add_f32_dpp v115, v115, v115 row_half_mirror row_mask:0xf bank_mask:0xf bound_ctrl:1
	v_sub_f32_e32 v124, v120, v112
	v_sub_f32_e32 v125, v121, v113
	v_sub_f32_e32 v126, v122, v114
	v_sub_f32_e32 v127, v123, v115
	v_fma_f32 v125, -v146, v124, v125
	v_fma_f32 v126, -v147, v124, v126
	v_fma_f32 v127, -v149, v124, v127
	s_waitcnt lgkmcnt(13)
	v_mul_f32_e32 v108, v206, v100
	s_waitcnt lgkmcnt(11)
	v_mul_f32_e32 v109, v214, v100
	v_fma_f32 v126, -v148, v125, v126
	v_fma_f32 v127, -v150, v125, v127
	s_waitcnt lgkmcnt(9)
	v_mul_f32_e32 v110, v222, v100
	s_waitcnt lgkmcnt(7)
	v_mul_f32_e32 v111, v230, v100
	v_fma_f32 v127, -v151, v126, v127
	v_fmac_f32_e32 v108, v207, v101
	v_fmac_f32_e32 v109, v215, v101
	v_cndmask_b32_e64 v106, v106, v124, s[14:15]
	v_fmac_f32_e32 v110, v223, v101
	v_cndmask_b32_e64 v106, v106, v125, s[16:17]
	v_fmac_f32_e32 v111, v231, v101
	v_cndmask_b32_e64 v106, v106, v126, s[18:19]
	v_fmac_f32_e32 v108, v208, v102
	v_cndmask_b32_e64 v106, v106, v127, s[20:21]
	v_fmac_f32_e32 v109, v216, v102
	v_fmac_f32_e32 v110, v224, v102
	v_fmac_f32_e32 v111, v232, v102
	v_fmac_f32_e32 v108, v209, v103
	v_fmac_f32_e32 v109, v217, v103
	v_fmac_f32_e32 v110, v225, v103
	v_fmac_f32_e32 v111, v233, v103
	v_fmac_f32_e32 v108, v210, v104
	v_fmac_f32_e32 v109, v218, v104
	v_fmac_f32_e32 v110, v226, v104
	s_waitcnt lgkmcnt(6)
	v_fmac_f32_e32 v111, v234, v104
	v_fmac_f32_e32 v108, v211, v105
	v_fmac_f32_e32 v109, v219, v105
	v_fmac_f32_e32 v110, v227, v105
	v_fmac_f32_e32 v111, v235, v105
	v_fmac_f32_e32 v108, v212, v106
	v_fmac_f32_e32 v109, v220, v106
	v_fmac_f32_e32 v110, v228, v106
	v_fmac_f32_e32 v111, v236, v106
	s_waitcnt lgkmcnt(0)
	ds_read_b128 v[176:179], v128 offset:15360
	ds_read_b128 v[180:183], v128 offset:15376
	ds_read_b128 v[184:187], v128 offset:15616
	ds_read_b128 v[188:191], v128 offset:15632
	ds_read_b128 v[192:195], v128 offset:15872
	ds_read_b128 v[196:199], v128 offset:15888
	ds_read_b128 v[200:203], v128 offset:16128
	ds_read_b128 v[238:241], v128 offset:16144
	ds_read_b32 v146, v129 offset:15772
	ds_read_b32 v147, v129 offset:16028
	ds_read_b32 v148, v129 offset:16060
	ds_read_b32 v149, v129 offset:16284
	ds_read_b32 v150, v129 offset:16316
	ds_read_b32 v151, v129 offset:16348
	v_add_f32_dpp v108, v108, v108 quad_perm:[1,0,3,2] row_mask:0xf bank_mask:0xf bound_ctrl:1
	v_add_f32_dpp v109, v109, v109 quad_perm:[1,0,3,2] row_mask:0xf bank_mask:0xf bound_ctrl:1
	v_cmp_eq_u32_e32 vcc, 60, v0
	v_add_f32_dpp v110, v110, v110 quad_perm:[1,0,3,2] row_mask:0xf bank_mask:0xf bound_ctrl:1
	v_add_f32_dpp v111, v111, v111 quad_perm:[1,0,3,2] row_mask:0xf bank_mask:0xf bound_ctrl:1
	v_cndmask_b32_e64 v120, 0, 1.0, vcc
	v_cmp_eq_u32_e32 vcc, 61, v0
	v_add_f32_dpp v108, v108, v108 quad_perm:[2,3,0,1] row_mask:0xf bank_mask:0xf bound_ctrl:1
	v_add_f32_dpp v109, v109, v109 quad_perm:[2,3,0,1] row_mask:0xf bank_mask:0xf bound_ctrl:1
	v_cndmask_b32_e64 v121, 0, 1.0, vcc
	v_cmp_eq_u32_e32 vcc, 62, v0
	v_add_f32_dpp v110, v110, v110 quad_perm:[2,3,0,1] row_mask:0xf bank_mask:0xf bound_ctrl:1
	v_add_f32_dpp v111, v111, v111 quad_perm:[2,3,0,1] row_mask:0xf bank_mask:0xf bound_ctrl:1
	v_cndmask_b32_e64 v122, 0, 1.0, vcc
	v_cmp_eq_u32_e32 vcc, 63, v0
	v_add_f32_dpp v108, v108, v108 row_half_mirror row_mask:0xf bank_mask:0xf bound_ctrl:1
	v_add_f32_dpp v109, v109, v109 row_half_mirror row_mask:0xf bank_mask:0xf bound_ctrl:1
	v_cndmask_b32_e64 v123, 0, 1.0, vcc
	v_add_f32_dpp v110, v110, v110 row_half_mirror row_mask:0xf bank_mask:0xf bound_ctrl:1
	v_add_f32_dpp v111, v111, v111 row_half_mirror row_mask:0xf bank_mask:0xf bound_ctrl:1
	v_sub_f32_e32 v124, v116, v108
	v_sub_f32_e32 v125, v117, v109
	v_sub_f32_e32 v126, v118, v110
	v_sub_f32_e32 v127, v119, v111
	v_fma_f32 v125, -v130, v124, v125
	v_fma_f32 v126, -v131, v124, v126
	v_fma_f32 v127, -v133, v124, v127
	s_waitcnt lgkmcnt(13)
	v_mul_f32_e32 v112, v176, v100
	s_waitcnt lgkmcnt(11)
	v_mul_f32_e32 v113, v184, v100
	v_fma_f32 v126, -v132, v125, v126
	v_fma_f32 v127, -v134, v125, v127
	s_waitcnt lgkmcnt(9)
	v_mul_f32_e32 v114, v192, v100
	s_waitcnt lgkmcnt(7)
	v_mul_f32_e32 v115, v200, v100
	v_fma_f32 v127, -v135, v126, v127
	v_fmac_f32_e32 v112, v177, v101
	v_fmac_f32_e32 v113, v185, v101
	v_cndmask_b32_e64 v107, v107, v124, s[6:7]
	v_fmac_f32_e32 v114, v193, v101
	v_cndmask_b32_e64 v107, v107, v125, s[8:9]
	v_fmac_f32_e32 v115, v201, v101
	v_cndmask_b32_e64 v107, v107, v126, s[10:11]
	v_fmac_f32_e32 v112, v178, v102
	v_cndmask_b32_e64 v107, v107, v127, s[12:13]
	v_fmac_f32_e32 v113, v186, v102
	v_fmac_f32_e32 v114, v194, v102
	v_fmac_f32_e32 v115, v202, v102
	v_fmac_f32_e32 v112, v179, v103
	v_fmac_f32_e32 v113, v187, v103
	v_fmac_f32_e32 v114, v195, v103
	v_fmac_f32_e32 v115, v203, v103
	v_fmac_f32_e32 v112, v180, v104
	v_fmac_f32_e32 v113, v188, v104
	v_fmac_f32_e32 v114, v196, v104
	s_waitcnt lgkmcnt(6)
	v_fmac_f32_e32 v115, v238, v104
	v_fmac_f32_e32 v112, v181, v105
	v_fmac_f32_e32 v113, v189, v105
	v_fmac_f32_e32 v114, v197, v105
	v_fmac_f32_e32 v115, v239, v105
	v_fmac_f32_e32 v112, v182, v106
	v_fmac_f32_e32 v113, v190, v106
	v_fmac_f32_e32 v114, v198, v106
	v_fmac_f32_e32 v115, v240, v106
	v_fmac_f32_e32 v112, v183, v107
	v_fmac_f32_e32 v113, v191, v107
	v_fmac_f32_e32 v114, v199, v107
	v_fmac_f32_e32 v115, v241, v107
	v_add_f32_dpp v112, v112, v112 quad_perm:[1,0,3,2] row_mask:0xf bank_mask:0xf bound_ctrl:1
	v_add_f32_dpp v113, v113, v113 quad_perm:[1,0,3,2] row_mask:0xf bank_mask:0xf bound_ctrl:1
	v_add_f32_dpp v114, v114, v114 quad_perm:[1,0,3,2] row_mask:0xf bank_mask:0xf bound_ctrl:1
	v_add_f32_dpp v115, v115, v115 quad_perm:[1,0,3,2] row_mask:0xf bank_mask:0xf bound_ctrl:1
	v_add_f32_dpp v112, v112, v112 quad_perm:[2,3,0,1] row_mask:0xf bank_mask:0xf bound_ctrl:1
	v_add_f32_dpp v113, v113, v113 quad_perm:[2,3,0,1] row_mask:0xf bank_mask:0xf bound_ctrl:1
	v_add_f32_dpp v114, v114, v114 quad_perm:[2,3,0,1] row_mask:0xf bank_mask:0xf bound_ctrl:1
	v_add_f32_dpp v115, v115, v115 quad_perm:[2,3,0,1] row_mask:0xf bank_mask:0xf bound_ctrl:1
	v_add_f32_dpp v112, v112, v112 row_half_mirror row_mask:0xf bank_mask:0xf bound_ctrl:1
	v_add_f32_dpp v113, v113, v113 row_half_mirror row_mask:0xf bank_mask:0xf bound_ctrl:1
	v_add_f32_dpp v114, v114, v114 row_half_mirror row_mask:0xf bank_mask:0xf bound_ctrl:1
	v_add_f32_dpp v115, v115, v115 row_half_mirror row_mask:0xf bank_mask:0xf bound_ctrl:1
	v_sub_f32_e32 v124, v120, v112
	v_sub_f32_e32 v125, v121, v113
	v_sub_f32_e32 v126, v122, v114
	v_sub_f32_e32 v127, v123, v115
	s_waitcnt lgkmcnt(5)
	v_fma_f32 v125, -v146, v124, v125
	s_waitcnt lgkmcnt(4)
	v_fma_f32 v126, -v147, v124, v126
	s_waitcnt lgkmcnt(2)
	v_fma_f32 v127, -v149, v124, v127
	v_fma_f32 v126, -v148, v125, v126
	s_waitcnt lgkmcnt(1)
	v_fma_f32 v127, -v150, v125, v127
	s_waitcnt lgkmcnt(0)
	v_fma_f32 v127, -v151, v126, v127
	v_cndmask_b32_e64 v107, v107, v124, s[14:15]
	v_cndmask_b32_e64 v107, v107, v125, s[16:17]
	v_cndmask_b32_e64 v107, v107, v126, s[18:19]
	v_cndmask_b32_e64 v107, v107, v127, s[20:21]
	v_lshl_add_u32 v152, v0, 2, 0
	v_add_u32_e32 v153, 0x15c00, v152
	v_add_u32_e32 v154, 0x15e00, v152
	v_add_u32_e32 v155, 0x15f00, v152
	ds_read_b32 v153, v153
	ds_read_b32 v154, v154
	ds_read_b32 v155, v155
	v_mul_u32_u24_e32 v156, 0x48, v2
	v_add_lshl_u32 v156, v0, v156, 1
	v_readlane_b32 s6, v244, 27
	v_readlane_b32 s7, v244, 32
	s_lshl_b64 s[8:9], s[36:37], 14
	s_mov_b32 s36, s2
	s_nop 1
	v_add_u32_e32 v157, s6, v156
	v_add_u32_e32 v156, s7, v156
	s_waitcnt lgkmcnt(0)
	v_mul_f32_e32 v154, v153, v154
	v_mul_f32_e32 v154, v154, v155
	v_mul_f32_e32 v158, v100, v153
	v_mul_f32_e32 v159, v100, v154
	v_cvt_pk_bf16_f32 v158, v158, v158
	v_cvt_pk_bf16_f32 v159, v159, v159
	ds_write_b16 v157, v158 offset:0
	ds_write_b16 v156, v159 offset:0
	v_mul_f32_e32 v158, v101, v153
	v_mul_f32_e32 v159, v101, v154
	v_cvt_pk_bf16_f32 v158, v158, v158
	v_cvt_pk_bf16_f32 v159, v159, v159
	ds_write_b16 v157, v158 offset:1152
	ds_write_b16 v156, v159 offset:1152
	v_mul_f32_e32 v158, v102, v153
	v_mul_f32_e32 v159, v102, v154
	v_cvt_pk_bf16_f32 v158, v158, v158
	v_cvt_pk_bf16_f32 v159, v159, v159
	ds_write_b16 v157, v158 offset:2304
	ds_write_b16 v156, v159 offset:2304
	v_mul_f32_e32 v158, v103, v153
	v_mul_f32_e32 v159, v103, v154
	v_cvt_pk_bf16_f32 v158, v158, v158
	v_cvt_pk_bf16_f32 v159, v159, v159
	ds_write_b16 v157, v158 offset:3456
	ds_write_b16 v156, v159 offset:3456
	v_mul_f32_e32 v158, v104, v153
	v_mul_f32_e32 v159, v104, v154
	v_cvt_pk_bf16_f32 v158, v158, v158
	v_cvt_pk_bf16_f32 v159, v159, v159
	ds_write_b16 v157, v158 offset:4608
	ds_write_b16 v156, v159 offset:4608
	v_mul_f32_e32 v158, v105, v153
	v_mul_f32_e32 v159, v105, v154
	v_cvt_pk_bf16_f32 v158, v158, v158
	v_cvt_pk_bf16_f32 v159, v159, v159
	ds_write_b16 v157, v158 offset:5760
	ds_write_b16 v156, v159 offset:5760
	v_mul_f32_e32 v158, v106, v153
	v_mul_f32_e32 v159, v106, v154
	v_cvt_pk_bf16_f32 v158, v158, v158
	v_cvt_pk_bf16_f32 v159, v159, v159
	ds_write_b16 v157, v158 offset:6912
	ds_write_b16 v156, v159 offset:6912
	v_mul_f32_e32 v158, v107, v153
	v_mul_f32_e32 v159, v107, v154
	v_cvt_pk_bf16_f32 v158, v158, v158
	v_cvt_pk_bf16_f32 v159, v159, v159
	ds_write_b16 v157, v158 offset:8064
	ds_write_b16 v156, v159 offset:8064
	v_mul_u32_u24_e32 v0, 0x48, v46
	v_lshlrev_b32_e32 v0, 1, v0
	v_add3_u32 v84, s6, v0, v48
	s_waitcnt lgkmcnt(0)
	s_barrier
	ds_read_b128 v[2:5], v84
	v_lshl_or_b32 v46, v43, 4, v46
	s_movk_i32 s6, 0x90
	v_mul_lo_u32 v6, v46, s6
	v_add3_u32 v56, 0, v6, v48
	ds_read_b128 v[6:9], v56 offset:35840
	ds_read_b128 v[10:13], v84 offset:64
	ds_read_b128 v[14:17], v56 offset:35904
	s_waitcnt lgkmcnt(2)
	v_mfma_f32_16x16x32_bf16 v[2:5], v[2:5], v[6:9], 0
	v_add3_u32 v0, s7, v0, v48
	ds_read_b128 v[42:45], v0
	ds_read_b128 v[48:51], v56 offset:17408
	ds_read_b128 v[52:55], v0 offset:64
	s_add_u32 s6, s22, s8
	s_waitcnt lgkmcnt(3)
	v_mfma_f32_16x16x32_bf16 v[2:5], v[10:13], v[14:17], v[2:5]
	ds_read_b128 v[10:13], v56 offset:17472
	s_addc_u32 s7, s23, s9
	v_lshl_add_u32 v46, v47, 7, v46
	s_waitcnt lgkmcnt(2)
	v_mfma_f32_16x16x32_bf16 v[42:45], v[42:45], v[48:51], 0
	ds_read_b128 v[60:63], v0 offset:2304
	ds_read_b128 v[64:67], v0 offset:2368
	s_add_u32 s8, s59, s8
	s_waitcnt lgkmcnt(2)
	v_mfma_f32_16x16x32_bf16 v[42:45], v[52:55], v[10:13], v[42:45]
	v_ashrrev_i32_e32 v47, 31, v46
	s_addc_u32 s9, s64, s9
	v_lshlrev_b64 v[56:57], 1, v[46:47]
	v_cvt_pk_bf16_f32 v2, v2, s0
	v_lshl_add_u64 v[80:81], s[8:9], 0, v[56:57]
	ds_read_b128 v[52:55], v84 offset:2304
	global_store_short v[80:81], v2, off
	s_nop 0
	v_cvt_pk_bf16_f32 v2, v42, s0
	v_lshl_add_u64 v[82:83], s[6:7], 0, v[56:57]
	global_store_short v[82:83], v2, off
	v_cvt_pk_bf16_f32 v2, v3, s0
	global_store_short v[80:81], v2, off offset:256
	v_cvt_pk_bf16_f32 v2, v43, s0
	ds_read_b128 v[56:59], v84 offset:2368
	global_store_short v[82:83], v2, off offset:256
	v_cvt_pk_bf16_f32 v2, v4, s0
	global_store_short v[80:81], v2, off offset:512
	v_cvt_pk_bf16_f32 v2, v44, s0
	global_store_short v[82:83], v2, off offset:512
	v_cvt_pk_bf16_f32 v42, v5, s0
	s_waitcnt lgkmcnt(3)
	v_mfma_f32_16x16x32_bf16 v[2:5], v[60:63], v[48:51], 0
	global_store_short v[80:81], v42, off offset:768
	v_cvt_pk_bf16_f32 v42, v45, s0
	global_store_short v[82:83], v42, off offset:768
	s_waitcnt lgkmcnt(1)
	v_mfma_f32_16x16x32_bf16 v[52:55], v[52:55], v[6:9], 0
	v_add_u32_e32 v42, 0x800, v46
	v_ashrrev_i32_e32 v43, 31, v42
	v_lshlrev_b64 v[42:43], 1, v[42:43]
	v_mfma_f32_16x16x32_bf16 v[2:5], v[64:67], v[10:13], v[2:5]
	v_lshl_add_u64 v[44:45], s[8:9], 0, v[42:43]
	v_lshl_add_u64 v[42:43], s[6:7], 0, v[42:43]
	ds_read_b128 v[60:63], v0 offset:4672
	s_waitcnt lgkmcnt(1)
	v_mfma_f32_16x16x32_bf16 v[52:55], v[56:59], v[14:17], v[52:55]
	ds_read_b128 v[56:59], v84 offset:4672
	s_nop 1
	v_cvt_pk_bf16_f32 v2, v2, s0
	global_store_short v[42:43], v2, off
	v_add_u32_e32 v42, 0x880, v46
	v_ashrrev_i32_e32 v43, 31, v42
	s_nop 0
	v_cvt_pk_bf16_f32 v47, v52, s0
	v_lshlrev_b64 v[42:43], 1, v[42:43]
	global_store_short v[44:45], v47, off
	v_cvt_pk_bf16_f32 v2, v53, s0
	v_lshl_add_u64 v[44:45], s[8:9], 0, v[42:43]
	global_store_short v[44:45], v2, off
	v_cvt_pk_bf16_f32 v44, v3, s0
	v_lshl_add_u64 v[2:3], s[6:7], 0, v[42:43]
	global_store_short v[2:3], v44, off
	v_add_u32_e32 v2, 0x900, v46
	v_ashrrev_i32_e32 v3, 31, v2
	v_lshlrev_b64 v[2:3], 1, v[2:3]
	ds_read_b128 v[42:45], v84 offset:4608
	v_cvt_pk_bf16_f32 v47, v54, s0
	v_lshl_add_u64 v[52:53], s[8:9], 0, v[2:3]
	v_cvt_pk_bf16_f32 v4, v4, s0
	v_lshl_add_u64 v[2:3], s[6:7], 0, v[2:3]
	global_store_short v[52:53], v47, off
	global_store_short v[2:3], v4, off
	v_cvt_pk_bf16_f32 v4, v55, s0
	ds_read_b128 v[52:55], v0 offset:4608
	s_waitcnt lgkmcnt(1)
	v_mfma_f32_16x16x32_bf16 v[42:45], v[42:45], v[6:9], 0
	v_add_u32_e32 v2, 0x980, v46
	v_ashrrev_i32_e32 v3, 31, v2
	v_lshlrev_b64 v[2:3], 1, v[2:3]
	s_waitcnt lgkmcnt(0)
	v_mfma_f32_16x16x32_bf16 v[52:55], v[52:55], v[48:51], 0
	s_and_b64 vcc, exec, s[38:39]
	v_mfma_f32_16x16x32_bf16 v[42:45], v[56:59], v[14:17], v[42:45]
	v_lshl_add_u64 v[56:57], s[8:9], 0, v[2:3]
	global_store_short v[56:57], v4, off
	v_cvt_pk_bf16_f32 v4, v5, s0
	v_lshl_add_u64 v[2:3], s[6:7], 0, v[2:3]
	global_store_short v[2:3], v4, off
	v_mfma_f32_16x16x32_bf16 v[2:5], v[60:63], v[10:13], v[52:55]
	s_nop 1
	v_cvt_pk_bf16_f32 v42, v42, s0
	v_cvt_pk_bf16_f32 v44, v44, s0
	ds_read_b128 v[56:59], v84 offset:6976
	v_add_u32_e32 v52, 0x1000, v46
	v_ashrrev_i32_e32 v53, 31, v52
	v_lshlrev_b64 v[52:53], 1, v[52:53]
	v_lshl_add_u64 v[54:55], s[8:9], 0, v[52:53]
	global_store_short v[54:55], v42, off
	v_cvt_pk_bf16_f32 v2, v2, s0
	v_lshl_add_u64 v[52:53], s[6:7], 0, v[52:53]
	v_add_u32_e32 v42, 0x1080, v46
	global_store_short v[52:53], v2, off
	v_cvt_pk_bf16_f32 v2, v43, s0
	v_ashrrev_i32_e32 v43, 31, v42
	v_lshlrev_b64 v[42:43], 1, v[42:43]
	v_lshl_add_u64 v[52:53], s[8:9], 0, v[42:43]
	global_store_short v[52:53], v2, off
	v_cvt_pk_bf16_f32 v47, v3, s0
	v_lshl_add_u64 v[2:3], s[6:7], 0, v[42:43]
	ds_read_b128 v[52:55], v84 offset:6912
	global_store_short v[2:3], v47, off
	v_add_u32_e32 v2, 0x1100, v46
	v_ashrrev_i32_e32 v3, 31, v2
	v_lshlrev_b64 v[2:3], 1, v[2:3]
	v_lshl_add_u64 v[42:43], s[8:9], 0, v[2:3]
	v_cvt_pk_bf16_f32 v4, v4, s0
	v_lshl_add_u64 v[2:3], s[6:7], 0, v[2:3]
	global_store_short v[42:43], v44, off
	global_store_short v[2:3], v4, off
	v_cvt_pk_bf16_f32 v4, v45, s0
	ds_read_b128 v[42:45], v0 offset:6912
	s_waitcnt lgkmcnt(1)
	v_mfma_f32_16x16x32_bf16 v[6:9], v[52:55], v[6:9], 0
	ds_read_b128 v[52:55], v0 offset:6976
	v_add_u32_e32 v2, 0x1180, v46
	v_ashrrev_i32_e32 v3, 31, v2
	v_lshlrev_b64 v[2:3], 1, v[2:3]
	v_mfma_f32_16x16x32_bf16 v[6:9], v[56:59], v[14:17], v[6:9]
	v_lshl_add_u64 v[14:15], s[8:9], 0, v[2:3]
	global_store_short v[14:15], v4, off
	v_cvt_pk_bf16_f32 v0, v5, s0
	s_waitcnt lgkmcnt(1)
	v_mfma_f32_16x16x32_bf16 v[14:17], v[42:45], v[48:51], 0
	v_lshl_add_u64 v[2:3], s[6:7], 0, v[2:3]
	global_store_short v[2:3], v0, off
	s_nop 0
	v_cvt_pk_bf16_f32 v0, v6, s0
	s_waitcnt lgkmcnt(0)
	v_mfma_f32_16x16x32_bf16 v[2:5], v[52:55], v[10:13], v[14:17]
	v_add_u32_e32 v10, 0x1800, v46
	v_ashrrev_i32_e32 v11, 31, v10
	v_lshlrev_b64 v[10:11], 1, v[10:11]
	v_lshl_add_u64 v[12:13], s[8:9], 0, v[10:11]
	global_store_short v[12:13], v0, off
	s_nop 2
	v_cvt_pk_bf16_f32 v0, v2, s0
	v_lshl_add_u64 v[10:11], s[6:7], 0, v[10:11]
	v_add_u32_e32 v6, 0x1880, v46
	global_store_short v[10:11], v0, off
	v_cvt_pk_bf16_f32 v0, v7, s0
	v_ashrrev_i32_e32 v7, 31, v6
	v_lshlrev_b64 v[6:7], 1, v[6:7]
	v_lshl_add_u64 v[10:11], s[8:9], 0, v[6:7]
	global_store_short v[10:11], v0, off
	v_cvt_pk_bf16_f32 v0, v3, s0
	v_lshl_add_u64 v[2:3], s[6:7], 0, v[6:7]
	global_store_short v[2:3], v0, off
	v_add_u32_e32 v2, 0x1900, v46
	v_ashrrev_i32_e32 v3, 31, v2
	v_lshlrev_b64 v[2:3], 1, v[2:3]
	v_cvt_pk_bf16_f32 v0, v8, s0
	v_lshl_add_u64 v[6:7], s[8:9], 0, v[2:3]
	global_store_short v[6:7], v0, off
	v_cvt_pk_bf16_f32 v0, v4, s0
	v_lshl_add_u64 v[2:3], s[6:7], 0, v[2:3]
	global_store_short v[2:3], v0, off
	v_add_u32_e32 v2, 0x1980, v46
	v_ashrrev_i32_e32 v3, 31, v2
	v_lshlrev_b64 v[2:3], 1, v[2:3]
	v_cvt_pk_bf16_f32 v0, v9, s0
	v_lshl_add_u64 v[6:7], s[8:9], 0, v[2:3]
	global_store_short v[6:7], v0, off
	v_cvt_pk_bf16_f32 v0, v5, s0
	v_lshl_add_u64 v[2:3], s[6:7], 0, v[2:3]
	global_store_short v[2:3], v0, off
	s_cbranch_vccnz .LBB0_601
